# nt (streaming) cache policy on stores of final outputs that are never re-read (y in phase 10, new retention state of the sample group)
# baseline (speedup 1.0000x reference)
.LBB0_712:
	s_or_b64 exec, exec, s[10:11]
	s_lshl_b32 s10, s16, 15
	s_mov_b32 s11, s95
	s_lshl_b64 s[16:17], s[10:11], 2
	s_add_u32 s10, s85, s16
	v_readlane_b32 s11, v252, 49
	v_mul_f32_e32 v8, 0x3fb8aa3b, v8
	s_addc_u32 s11, s11, s17
	v_ashrrev_i32_e32 v85, 6, v83
	v_exp_f32_e32 v84, v8
	v_lshlrev_b32_e32 v8, 2, v81
	s_add_u32 s16, s64, s16
	s_waitcnt vmcnt(1)
	v_lshlrev_b32_e32 v74, 16, v2
	v_and_b32_e32 v75, 0xffff0000, v2
	v_lshlrev_b32_e32 v2, 4, v85
	s_addc_u32 s17, s65, s17
	v_lshlrev_b32_e32 v76, 16, v3
	v_and_b32_e32 v77, 0xffff0000, v3
	v_lshlrev_b32_e32 v176, 2, v8
	v_ashrrev_i32_e32 v3, 31, v2
	s_waitcnt vmcnt(0)
	v_lshlrev_b32_e32 v88, 16, v0
	v_and_b32_e32 v89, 0xffff0000, v0
	v_lshlrev_b32_e32 v90, 16, v1
	v_and_b32_e32 v91, 0xffff0000, v1
	v_lshl_add_u64 v[0:1], s[16:17], 0, v[176:177]
	v_lshlrev_b64 v[78:79], 10, v[2:3]
	v_lshlrev_b32_e32 v70, 16, v4
	v_and_b32_e32 v71, 0xffff0000, v4
	v_lshlrev_b32_e32 v72, 16, v5
	v_and_b32_e32 v73, 0xffff0000, v5
	v_lshl_add_u64 v[4:5], v[0:1], 0, v[78:79]
	global_load_dwordx4 v[54:57], v[4:5], off
	v_or_b32_e32 v4, 1, v2
	v_ashrrev_i32_e32 v5, 31, v4
	v_lshlrev_b64 v[150:151], 10, v[4:5]
	v_lshl_add_u64 v[4:5], v[0:1], 0, v[150:151]
	global_load_dwordx4 v[58:61], v[4:5], off
	v_or_b32_e32 v4, 2, v2
	v_ashrrev_i32_e32 v5, 31, v4
	v_lshlrev_b64 v[152:153], 10, v[4:5]
	v_lshl_add_u64 v[4:5], v[0:1], 0, v[152:153]
	global_load_dwordx4 v[62:65], v[4:5], off
	v_or_b32_e32 v4, 3, v2
	v_ashrrev_i32_e32 v5, 31, v4
	v_lshlrev_b64 v[52:53], 10, v[4:5]
	v_lshl_add_u64 v[4:5], v[0:1], 0, v[52:53]
	global_load_dwordx4 v[48:51], v[4:5], off
	v_or_b32_e32 v4, 4, v2
	v_ashrrev_i32_e32 v5, 31, v4
	v_lshlrev_b64 v[128:129], 10, v[4:5]
	v_lshl_add_u64 v[4:5], v[0:1], 0, v[128:129]
	global_load_dwordx4 v[44:47], v[4:5], off
	v_or_b32_e32 v4, 5, v2
	v_ashrrev_i32_e32 v5, 31, v4
	v_lshlrev_b64 v[126:127], 10, v[4:5]
	v_lshl_add_u64 v[4:5], v[0:1], 0, v[126:127]
	global_load_dwordx4 v[40:43], v[4:5], off
	v_or_b32_e32 v4, 6, v2
	v_ashrrev_i32_e32 v5, 31, v4
	v_lshlrev_b64 v[124:125], 10, v[4:5]
	v_lshl_add_u64 v[4:5], v[0:1], 0, v[124:125]
	global_load_dwordx4 v[36:39], v[4:5], off
	v_or_b32_e32 v4, 7, v2
	v_ashrrev_i32_e32 v5, 31, v4
	v_lshlrev_b64 v[122:123], 10, v[4:5]
	v_lshl_add_u64 v[4:5], v[0:1], 0, v[122:123]
	global_load_dwordx4 v[32:35], v[4:5], off
	v_or_b32_e32 v4, 8, v2
	v_ashrrev_i32_e32 v5, 31, v4
	v_lshlrev_b64 v[120:121], 10, v[4:5]
	v_lshl_add_u64 v[4:5], v[0:1], 0, v[120:121]
	global_load_dwordx4 v[28:31], v[4:5], off
	v_or_b32_e32 v4, 9, v2
	v_ashrrev_i32_e32 v5, 31, v4
	v_lshlrev_b64 v[118:119], 10, v[4:5]
	v_lshl_add_u64 v[4:5], v[0:1], 0, v[118:119]
	global_load_dwordx4 v[24:27], v[4:5], off
	v_or_b32_e32 v4, 10, v2
	v_ashrrev_i32_e32 v5, 31, v4
	v_mul_f32_e32 v86, v84, v84
	v_lshlrev_b64 v[116:117], 10, v[4:5]
	v_mul_f32_e32 v80, v84, v86
	v_lshlrev_b32_e32 v66, 16, v6
	v_and_b32_e32 v67, 0xffff0000, v6
	v_lshl_add_u64 v[4:5], v[0:1], 0, v[116:117]
	global_load_dwordx4 v[20:23], v[4:5], off
	v_or_b32_e32 v4, 11, v2
	v_pk_mul_f32 v[106:107], v[80:81], v[66:67] op_sel_hi:[0,1]
	v_and_b32_e32 v66, 0xffffffc0, v83
	v_ashrrev_i32_e32 v5, 31, v4
	v_pk_mul_f32 v[100:101], v[86:87], v[70:71] op_sel_hi:[0,1]
	v_pk_mul_f32 v[104:105], v[86:87], v[72:73] op_sel_hi:[0,1]
	v_add_u32_e32 v87, 0, v66
	v_lshlrev_b32_e32 v68, 16, v7
	v_and_b32_e32 v69, 0xffff0000, v7
	v_lshlrev_b64 v[114:115], 10, v[4:5]
	ds_read_b128 v[134:137], v87 offset:2048
	ds_read_b128 v[142:145], v87 offset:3072
	v_lshl_add_u64 v[4:5], v[0:1], 0, v[114:115]
	v_pk_mul_f32 v[98:99], v[80:81], v[68:69] op_sel_hi:[0,1]
	v_pk_mul_f32 v[96:97], v[84:85], v[74:75] op_sel_hi:[0,1]
	v_pk_mul_f32 v[102:103], v[84:85], v[76:77] op_sel_hi:[0,1]
	ds_read_b128 v[66:69], v87
	ds_read_b128 v[70:73], v87 offset:512
	ds_read_b128 v[74:77], v87 offset:1024
	ds_read_b128 v[130:133], v87 offset:1536
	global_load_dwordx4 v[16:19], v[4:5], off
	v_or_b32_e32 v4, 12, v2
	v_ashrrev_i32_e32 v5, 31, v4
	v_lshlrev_b64 v[112:113], 10, v[4:5]
	v_mul_f32_e32 v82, v86, v86
	v_lshl_add_u64 v[4:5], v[0:1], 0, v[112:113]
	s_waitcnt lgkmcnt(5)
	v_pk_mul_f32 v[138:139], v[106:107], v[134:135] op_sel_hi:[1,0]
	v_pk_mul_f32 v[140:141], v[98:99], v[134:135] op_sel_hi:[1,0]
	global_load_dwordx4 v[12:15], v[4:5], off
	v_or_b32_e32 v4, 13, v2
	s_waitcnt vmcnt(12) lgkmcnt(3)
	v_pk_fma_f32 v[154:155], v[56:57], v[66:67], 0 op_sel_hi:[1,0,0]
	v_pk_fma_f32 v[156:157], v[54:55], v[66:67], 0 op_sel_hi:[1,0,0]
	s_waitcnt lgkmcnt(2)
	v_pk_fma_f32 v[158:159], v[56:57], v[70:71], 0 op_sel_hi:[1,0,0]
	v_pk_fma_f32 v[160:161], v[54:55], v[70:71], 0 op_sel_hi:[1,0,0]
	s_waitcnt lgkmcnt(1)
	v_pk_fma_f32 v[162:163], v[56:57], v[74:75], 0 op_sel_hi:[1,0,0]
	v_pk_fma_f32 v[164:165], v[54:55], v[74:75], 0 op_sel_hi:[1,0,0]
	s_waitcnt lgkmcnt(0)
	v_pk_fma_f32 v[166:167], v[56:57], v[130:131], 0 op_sel_hi:[1,0,0]
	v_pk_fma_f32 v[168:169], v[54:55], v[130:131], 0 op_sel_hi:[1,0,0]
	v_pk_fma_f32 v[56:57], v[82:83], v[56:57], v[140:141] op_sel_hi:[0,1,1]
	v_pk_fma_f32 v[54:55], v[82:83], v[54:55], v[138:139] op_sel_hi:[0,1,1]
	ds_read_b128 v[138:141], v87 offset:2560
	ds_read_b128 v[146:149], v87 offset:3584
	v_ashrrev_i32_e32 v5, 31, v4
	v_lshlrev_b64 v[110:111], 10, v[4:5]
	v_lshl_add_u64 v[4:5], v[0:1], 0, v[110:111]
	global_load_dwordx4 v[8:11], v[4:5], off
	v_or_b32_e32 v4, 14, v2
	v_or_b32_e32 v2, 15, v2
	v_ashrrev_i32_e32 v5, 31, v4
	v_ashrrev_i32_e32 v3, 31, v2
	s_waitcnt lgkmcnt(1)
	v_pk_fma_f32 v[56:57], v[104:105], v[138:139], v[56:57] op_sel_hi:[1,0,1]
	v_pk_fma_f32 v[54:55], v[100:101], v[138:139], v[54:55] op_sel_hi:[1,0,1]
	v_lshlrev_b64 v[108:109], 10, v[4:5]
	v_lshlrev_b64 v[92:93], 10, v[2:3]
	v_lshl_add_u64 v[94:95], s[10:11], 0, v[176:177]
	v_pk_fma_f32 v[56:57], v[102:103], v[142:143], v[56:57] op_sel_hi:[1,0,1]
	v_pk_fma_f32 v[54:55], v[96:97], v[142:143], v[54:55] op_sel_hi:[1,0,1]
	v_lshl_add_u64 v[4:5], v[0:1], 0, v[108:109]
	v_lshl_add_u64 v[0:1], v[0:1], 0, v[92:93]
	s_waitcnt lgkmcnt(0)
	v_pk_fma_f32 v[56:57], v[146:147], v[90:91], v[56:57] op_sel_hi:[0,1,1]
	v_pk_fma_f32 v[54:55], v[146:147], v[88:89], v[54:55] op_sel_hi:[0,1,1]
	v_lshl_add_u64 v[78:79], v[94:95], 0, v[78:79]
	global_load_dwordx4 v[4:7], v[4:5], off
	v_lshl_add_u64 v[52:53], v[94:95], 0, v[52:53]
	global_load_dwordx4 v[0:3], v[0:1], off
	v_lshl_add_u64 v[128:129], v[94:95], 0, v[128:129]
	global_store_dwordx4 v[78:79], v[54:57], off nt
	s_waitcnt vmcnt(15)
	v_pk_fma_f32 v[78:79], v[60:61], v[66:67], v[154:155] op_sel:[0,1,0]
	v_pk_fma_f32 v[66:67], v[58:59], v[66:67], v[156:157] op_sel:[0,1,0]
	v_pk_mul_f32 v[54:55], v[106:107], v[134:135] op_sel:[0,1]
	v_pk_mul_f32 v[56:57], v[98:99], v[134:135] op_sel:[0,1]
	v_pk_fma_f32 v[54:55], v[82:83], v[58:59], v[54:55] op_sel_hi:[0,1,1]
	v_pk_fma_f32 v[56:57], v[82:83], v[60:61], v[56:57] op_sel_hi:[0,1,1]
	v_pk_fma_f32 v[56:57], v[104:105], v[138:139], v[56:57] op_sel:[0,1,0]
	v_pk_fma_f32 v[54:55], v[100:101], v[138:139], v[54:55] op_sel:[0,1,0]
	v_pk_fma_f32 v[56:57], v[102:103], v[142:143], v[56:57] op_sel:[0,1,0]
	v_pk_fma_f32 v[54:55], v[96:97], v[142:143], v[54:55] op_sel:[0,1,0]
	v_pk_fma_f32 v[154:155], v[60:61], v[70:71], v[158:159] op_sel:[0,1,0]
	v_pk_fma_f32 v[70:71], v[58:59], v[70:71], v[160:161] op_sel:[0,1,0]
	v_pk_fma_f32 v[156:157], v[60:61], v[74:75], v[162:163] op_sel:[0,1,0]
	v_pk_fma_f32 v[74:75], v[58:59], v[74:75], v[164:165] op_sel:[0,1,0]
	v_pk_fma_f32 v[158:159], v[60:61], v[130:131], v[166:167] op_sel:[0,1,0]
	v_pk_fma_f32 v[130:131], v[58:59], v[130:131], v[168:169] op_sel:[0,1,0]
	v_pk_fma_f32 v[56:57], v[146:147], v[90:91], v[56:57] op_sel:[1,0,0]
	v_pk_fma_f32 v[54:55], v[146:147], v[88:89], v[54:55] op_sel:[1,0,0]
	v_lshl_add_u64 v[58:59], v[94:95], 0, v[150:151]
	global_store_dwordx4 v[58:59], v[54:57], off nt
	s_waitcnt vmcnt(15)
	v_pk_fma_f32 v[60:61], v[62:63], v[68:69], v[66:67] op_sel_hi:[1,0,1]
	v_pk_fma_f32 v[70:71], v[62:63], v[72:73], v[70:71] op_sel_hi:[1,0,1]
	v_pk_mul_f32 v[54:55], v[106:107], v[136:137] op_sel_hi:[1,0]
	v_pk_mul_f32 v[56:57], v[98:99], v[136:137] op_sel_hi:[1,0]
	v_pk_fma_f32 v[54:55], v[82:83], v[62:63], v[54:55] op_sel_hi:[0,1,1]
	v_pk_fma_f32 v[56:57], v[82:83], v[64:65], v[56:57] op_sel_hi:[0,1,1]
	v_pk_fma_f32 v[56:57], v[104:105], v[140:141], v[56:57] op_sel_hi:[1,0,1]
	v_pk_fma_f32 v[54:55], v[100:101], v[140:141], v[54:55] op_sel_hi:[1,0,1]
	v_pk_fma_f32 v[56:57], v[102:103], v[144:145], v[56:57] op_sel_hi:[1,0,1]
	v_pk_fma_f32 v[54:55], v[96:97], v[144:145], v[54:55] op_sel_hi:[1,0,1]
	v_pk_fma_f32 v[74:75], v[62:63], v[76:77], v[74:75] op_sel_hi:[1,0,1]
	v_pk_fma_f32 v[130:131], v[62:63], v[132:133], v[130:131] op_sel_hi:[1,0,1]
	v_pk_fma_f32 v[56:57], v[148:149], v[90:91], v[56:57] op_sel_hi:[0,1,1]
	v_pk_fma_f32 v[54:55], v[148:149], v[88:89], v[54:55] op_sel_hi:[0,1,1]
	v_lshl_add_u64 v[62:63], v[94:95], 0, v[152:153]
	v_pk_fma_f32 v[58:59], v[64:65], v[68:69], v[78:79] op_sel_hi:[1,0,1]
	global_store_dwordx4 v[62:63], v[54:57], off nt
	v_pk_fma_f32 v[66:67], v[64:65], v[72:73], v[154:155] op_sel_hi:[1,0,1]
	v_pk_fma_f32 v[78:79], v[64:65], v[76:77], v[156:157] op_sel_hi:[1,0,1]
	v_mov_b32_e32 v54, v69
	s_waitcnt vmcnt(15)
	v_pk_fma_f32 v[56:57], v[50:51], v[54:55], v[58:59] op_sel_hi:[1,0,1]
	v_pk_fma_f32 v[58:59], v[48:49], v[54:55], v[60:61] op_sel_hi:[1,0,1]
	v_mov_b32_e32 v54, v73
	v_pk_fma_f32 v[60:61], v[50:51], v[54:55], v[66:67] op_sel_hi:[1,0,1]
	v_pk_fma_f32 v[62:63], v[48:49], v[54:55], v[70:71] op_sel_hi:[1,0,1]
	v_mov_b32_e32 v54, v77
	v_pk_fma_f32 v[134:135], v[64:65], v[132:133], v[158:159] op_sel_hi:[1,0,1]
	v_pk_fma_f32 v[64:65], v[50:51], v[54:55], v[78:79] op_sel_hi:[1,0,1]
	v_pk_fma_f32 v[66:67], v[48:49], v[54:55], v[74:75] op_sel_hi:[1,0,1]
	v_mov_b32_e32 v54, v133
	v_pk_fma_f32 v[68:69], v[50:51], v[54:55], v[134:135] op_sel_hi:[1,0,1]
	v_pk_fma_f32 v[70:71], v[48:49], v[54:55], v[130:131] op_sel_hi:[1,0,1]
	v_mov_b32_e32 v54, v137
	v_pk_mul_f32 v[72:73], v[106:107], v[54:55] op_sel_hi:[1,0]
	v_pk_mul_f32 v[54:55], v[98:99], v[54:55] op_sel_hi:[1,0]
	v_pk_fma_f32 v[48:49], v[82:83], v[48:49], v[72:73] op_sel_hi:[0,1,1]
	v_pk_fma_f32 v[50:51], v[82:83], v[50:51], v[54:55] op_sel_hi:[0,1,1]
	v_mov_b32_e32 v54, v141
	v_pk_fma_f32 v[50:51], v[104:105], v[54:55], v[50:51] op_sel_hi:[1,0,1]
	v_pk_fma_f32 v[48:49], v[100:101], v[54:55], v[48:49] op_sel_hi:[1,0,1]
	v_mov_b32_e32 v54, v145
	v_pk_fma_f32 v[50:51], v[102:103], v[54:55], v[50:51] op_sel_hi:[1,0,1]
	v_pk_fma_f32 v[48:49], v[96:97], v[54:55], v[48:49] op_sel_hi:[1,0,1]
	v_mov_b32_e32 v54, v149
	v_pk_fma_f32 v[50:51], v[54:55], v[90:91], v[50:51] op_sel_hi:[0,1,1]
	v_pk_fma_f32 v[48:49], v[54:55], v[88:89], v[48:49] op_sel_hi:[0,1,1]
	global_store_dwordx4 v[52:53], v[48:51], off nt
	ds_read_b128 v[52:55], v87 offset:16
	ds_read_b128 v[48:51], v87 offset:32
	v_lshl_add_u64 v[120:121], v[94:95], 0, v[120:121]
	v_cmp_gt_i32_e32 vcc, s84, v83
	s_waitcnt vmcnt(15) lgkmcnt(1)
	v_pk_fma_f32 v[130:131], v[46:47], v[52:53], v[56:57] op_sel_hi:[1,0,1]
	v_pk_fma_f32 v[132:133], v[44:45], v[52:53], v[58:59] op_sel_hi:[1,0,1]
	ds_read_b128 v[56:59], v87 offset:528
	s_waitcnt lgkmcnt(0)
	v_pk_fma_f32 v[134:135], v[46:47], v[56:57], v[60:61] op_sel_hi:[1,0,1]
	v_pk_fma_f32 v[136:137], v[44:45], v[56:57], v[62:63] op_sel_hi:[1,0,1]
	ds_read_b128 v[60:63], v87 offset:1040
	s_waitcnt lgkmcnt(0)
	v_pk_fma_f32 v[138:139], v[46:47], v[60:61], v[64:65] op_sel_hi:[1,0,1]
	v_pk_fma_f32 v[140:141], v[44:45], v[60:61], v[66:67] op_sel_hi:[1,0,1]
	ds_read_b128 v[64:67], v87 offset:1552
	s_waitcnt lgkmcnt(0)
	v_pk_fma_f32 v[142:143], v[46:47], v[64:65], v[68:69] op_sel_hi:[1,0,1]
	v_pk_fma_f32 v[144:145], v[44:45], v[64:65], v[70:71] op_sel_hi:[1,0,1]
	ds_read_b128 v[68:71], v87 offset:2064
	s_waitcnt lgkmcnt(0)
	v_pk_mul_f32 v[72:73], v[106:107], v[68:69] op_sel_hi:[1,0]
	v_pk_mul_f32 v[74:75], v[98:99], v[68:69] op_sel_hi:[1,0]
	v_pk_fma_f32 v[72:73], v[82:83], v[44:45], v[72:73] op_sel_hi:[0,1,1]
	v_pk_fma_f32 v[74:75], v[82:83], v[46:47], v[74:75] op_sel_hi:[0,1,1]
	ds_read_b128 v[44:47], v87 offset:2576
	s_waitcnt lgkmcnt(0)
	v_pk_fma_f32 v[76:77], v[104:105], v[44:45], v[74:75] op_sel_hi:[1,0,1]
	v_pk_fma_f32 v[78:79], v[100:101], v[44:45], v[72:73] op_sel_hi:[1,0,1]
	ds_read_b128 v[72:75], v87 offset:3088
	s_waitcnt lgkmcnt(0)
	v_pk_fma_f32 v[146:147], v[102:103], v[72:73], v[76:77] op_sel_hi:[1,0,1]
	v_pk_fma_f32 v[148:149], v[96:97], v[72:73], v[78:79] op_sel_hi:[1,0,1]
	ds_read_b128 v[76:79], v87 offset:3600
	s_waitcnt lgkmcnt(0)
	v_pk_fma_f32 v[150:151], v[76:77], v[90:91], v[146:147] op_sel_hi:[0,1,1]
	v_pk_fma_f32 v[148:149], v[76:77], v[88:89], v[148:149] op_sel_hi:[0,1,1]
	global_store_dwordx4 v[128:129], v[148:151], off nt
	s_waitcnt vmcnt(15)
	v_pk_fma_f32 v[128:129], v[42:43], v[52:53], v[130:131] op_sel:[0,1,0]
	v_pk_fma_f32 v[130:131], v[42:43], v[56:57], v[134:135] op_sel:[0,1,0]
	v_pk_fma_f32 v[56:57], v[40:41], v[56:57], v[136:137] op_sel:[0,1,0]
	v_pk_mul_f32 v[136:137], v[106:107], v[68:69] op_sel:[0,1]
	v_pk_mul_f32 v[68:69], v[98:99], v[68:69] op_sel:[0,1]
	v_pk_fma_f32 v[52:53], v[40:41], v[52:53], v[132:133] op_sel:[0,1,0]
	v_pk_fma_f32 v[132:133], v[42:43], v[60:61], v[138:139] op_sel:[0,1,0]
	v_pk_fma_f32 v[60:61], v[40:41], v[60:61], v[140:141] op_sel:[0,1,0]
	v_pk_fma_f32 v[134:135], v[42:43], v[64:65], v[142:143] op_sel:[0,1,0]
	v_pk_fma_f32 v[64:65], v[40:41], v[64:65], v[144:145] op_sel:[0,1,0]
	v_pk_fma_f32 v[42:43], v[82:83], v[42:43], v[68:69] op_sel_hi:[0,1,1]
	v_pk_fma_f32 v[40:41], v[82:83], v[40:41], v[136:137] op_sel_hi:[0,1,1]
	v_pk_fma_f32 v[42:43], v[104:105], v[44:45], v[42:43] op_sel:[0,1,0]
	v_pk_fma_f32 v[40:41], v[100:101], v[44:45], v[40:41] op_sel:[0,1,0]
	v_pk_fma_f32 v[42:43], v[102:103], v[72:73], v[42:43] op_sel:[0,1,0]
	v_pk_fma_f32 v[40:41], v[96:97], v[72:73], v[40:41] op_sel:[0,1,0]
	v_pk_fma_f32 v[42:43], v[76:77], v[90:91], v[42:43] op_sel:[1,0,0]
	v_pk_fma_f32 v[40:41], v[76:77], v[88:89], v[40:41] op_sel:[1,0,0]
	v_lshl_add_u64 v[44:45], v[94:95], 0, v[126:127]
	v_pk_mul_f32 v[72:73], v[106:107], v[70:71] op_sel_hi:[1,0]
	v_pk_mul_f32 v[76:77], v[98:99], v[70:71] op_sel_hi:[1,0]
	global_store_dwordx4 v[44:45], v[40:43], off nt
	s_waitcnt vmcnt(15)
	v_pk_fma_f32 v[44:45], v[38:39], v[58:59], v[130:131] op_sel_hi:[1,0,1]
	v_pk_fma_f32 v[60:61], v[36:37], v[62:63], v[60:61] op_sel_hi:[1,0,1]
	v_pk_fma_f32 v[40:41], v[38:39], v[54:55], v[128:129] op_sel_hi:[1,0,1]
	v_pk_fma_f32 v[42:43], v[36:37], v[54:55], v[52:53] op_sel_hi:[1,0,1]
	v_pk_fma_f32 v[52:53], v[36:37], v[58:59], v[56:57] op_sel_hi:[1,0,1]
	v_pk_fma_f32 v[56:57], v[38:39], v[62:63], v[132:133] op_sel_hi:[1,0,1]
	v_pk_fma_f32 v[68:69], v[38:39], v[66:67], v[134:135] op_sel_hi:[1,0,1]
	v_pk_fma_f32 v[64:65], v[36:37], v[66:67], v[64:65] op_sel_hi:[1,0,1]
	v_pk_fma_f32 v[38:39], v[82:83], v[38:39], v[76:77] op_sel_hi:[0,1,1]
	v_pk_fma_f32 v[36:37], v[82:83], v[36:37], v[72:73] op_sel_hi:[0,1,1]
	v_pk_fma_f32 v[38:39], v[104:105], v[46:47], v[38:39] op_sel_hi:[1,0,1]
	v_pk_fma_f32 v[36:37], v[100:101], v[46:47], v[36:37] op_sel_hi:[1,0,1]
	v_pk_fma_f32 v[38:39], v[102:103], v[74:75], v[38:39] op_sel_hi:[1,0,1]
	v_pk_fma_f32 v[36:37], v[96:97], v[74:75], v[36:37] op_sel_hi:[1,0,1]
	v_pk_fma_f32 v[38:39], v[78:79], v[90:91], v[38:39] op_sel_hi:[0,1,1]
	v_pk_fma_f32 v[36:37], v[78:79], v[88:89], v[36:37] op_sel_hi:[0,1,1]
	v_lshl_add_u64 v[72:73], v[94:95], 0, v[124:125]
	global_store_dwordx4 v[72:73], v[36:39], off nt
	v_mov_b32_e32 v46, v67
	s_nop 0
	v_mov_b32_e32 v36, v55
	s_waitcnt vmcnt(15)
	v_pk_fma_f32 v[38:39], v[34:35], v[36:37], v[40:41] op_sel_hi:[1,0,1]
	v_mov_b32_e32 v40, v59
	v_pk_fma_f32 v[36:37], v[32:33], v[36:37], v[42:43] op_sel_hi:[1,0,1]
	v_pk_fma_f32 v[42:43], v[34:35], v[40:41], v[44:45] op_sel_hi:[1,0,1]
	v_mov_b32_e32 v44, v63
	v_pk_fma_f32 v[40:41], v[32:33], v[40:41], v[52:53] op_sel_hi:[1,0,1]
	v_pk_fma_f32 v[52:53], v[34:35], v[44:45], v[56:57] op_sel_hi:[1,0,1]
	v_pk_fma_f32 v[54:55], v[34:35], v[46:47], v[68:69] op_sel_hi:[1,0,1]
	v_pk_fma_f32 v[56:57], v[32:33], v[46:47], v[64:65] op_sel_hi:[1,0,1]
	v_mov_b32_e32 v46, v71
	v_pk_fma_f32 v[44:45], v[32:33], v[44:45], v[60:61] op_sel_hi:[1,0,1]
	v_pk_mul_f32 v[58:59], v[106:107], v[46:47] op_sel_hi:[1,0]
	v_pk_mul_f32 v[60:61], v[98:99], v[46:47] op_sel_hi:[1,0]
	v_pk_fma_f32 v[32:33], v[82:83], v[32:33], v[58:59] op_sel_hi:[0,1,1]
	v_pk_fma_f32 v[34:35], v[82:83], v[34:35], v[60:61] op_sel_hi:[0,1,1]
	v_mov_b32_e32 v46, v47
	v_pk_fma_f32 v[34:35], v[104:105], v[46:47], v[34:35] op_sel_hi:[1,0,1]
	v_pk_fma_f32 v[32:33], v[100:101], v[46:47], v[32:33] op_sel_hi:[1,0,1]
	v_mov_b32_e32 v46, v75
	v_pk_fma_f32 v[34:35], v[102:103], v[46:47], v[34:35] op_sel_hi:[1,0,1]
	v_pk_fma_f32 v[32:33], v[96:97], v[46:47], v[32:33] op_sel_hi:[1,0,1]
	v_mov_b32_e32 v46, v79
	v_pk_fma_f32 v[34:35], v[46:47], v[90:91], v[34:35] op_sel_hi:[0,1,1]
	v_pk_fma_f32 v[32:33], v[46:47], v[88:89], v[32:33] op_sel_hi:[0,1,1]
	v_lshl_add_u64 v[46:47], v[94:95], 0, v[122:123]
	global_store_dwordx4 v[46:47], v[32:35], off nt
	s_waitcnt vmcnt(15)
	v_pk_fma_f32 v[64:65], v[30:31], v[48:49], v[38:39] op_sel_hi:[1,0,1]
	v_pk_fma_f32 v[66:67], v[28:29], v[48:49], v[36:37] op_sel_hi:[1,0,1]
	ds_read_b128 v[32:35], v87 offset:544
	ds_read_b128 v[36:39], v87 offset:1056
	ds_read_b128 v[60:63], v87 offset:3616
	s_waitcnt lgkmcnt(2)
	v_pk_fma_f32 v[68:69], v[30:31], v[32:33], v[42:43] op_sel_hi:[1,0,1]
	v_pk_fma_f32 v[70:71], v[28:29], v[32:33], v[40:41] op_sel_hi:[1,0,1]
	s_waitcnt lgkmcnt(1)
	v_pk_fma_f32 v[74:75], v[28:29], v[36:37], v[44:45] op_sel_hi:[1,0,1]
	ds_read_b128 v[40:43], v87 offset:1568
	ds_read_b128 v[44:47], v87 offset:2080
	v_pk_fma_f32 v[72:73], v[30:31], v[36:37], v[52:53] op_sel_hi:[1,0,1]
	s_waitcnt lgkmcnt(1)
	v_pk_fma_f32 v[76:77], v[30:31], v[40:41], v[54:55] op_sel_hi:[1,0,1]
	s_waitcnt lgkmcnt(0)
	v_pk_mul_f32 v[52:53], v[106:107], v[44:45] op_sel_hi:[1,0]
	v_pk_mul_f32 v[54:55], v[98:99], v[44:45] op_sel_hi:[1,0]
	v_pk_fma_f32 v[78:79], v[28:29], v[40:41], v[56:57] op_sel_hi:[1,0,1]
	v_pk_fma_f32 v[30:31], v[82:83], v[30:31], v[54:55] op_sel_hi:[0,1,1]
	v_pk_fma_f32 v[28:29], v[82:83], v[28:29], v[52:53] op_sel_hi:[0,1,1]
	ds_read_b128 v[52:55], v87 offset:2592
	ds_read_b128 v[56:59], v87 offset:3104
	s_waitcnt lgkmcnt(1)
	v_pk_fma_f32 v[30:31], v[104:105], v[52:53], v[30:31] op_sel_hi:[1,0,1]
	v_pk_fma_f32 v[28:29], v[100:101], v[52:53], v[28:29] op_sel_hi:[1,0,1]
	s_waitcnt lgkmcnt(0)
	v_pk_fma_f32 v[30:31], v[102:103], v[56:57], v[30:31] op_sel_hi:[1,0,1]
	v_pk_fma_f32 v[28:29], v[96:97], v[56:57], v[28:29] op_sel_hi:[1,0,1]
	v_pk_fma_f32 v[30:31], v[60:61], v[90:91], v[30:31] op_sel_hi:[0,1,1]
	v_pk_fma_f32 v[28:29], v[60:61], v[88:89], v[28:29] op_sel_hi:[0,1,1]
	global_store_dwordx4 v[120:121], v[28:31], off nt
	s_waitcnt vmcnt(15)
	s_nop 0
	v_pk_fma_f32 v[28:29], v[26:27], v[48:49], v[64:65] op_sel:[0,1,0]
	v_pk_fma_f32 v[30:31], v[24:25], v[48:49], v[66:67] op_sel:[0,1,0]
	v_pk_fma_f32 v[48:49], v[26:27], v[32:33], v[68:69] op_sel:[0,1,0]
	v_pk_mul_f32 v[68:69], v[106:107], v[44:45] op_sel:[0,1]
	v_pk_mul_f32 v[44:45], v[98:99], v[44:45] op_sel:[0,1]
	v_pk_fma_f32 v[32:33], v[24:25], v[32:33], v[70:71] op_sel:[0,1,0]
	v_pk_fma_f32 v[64:65], v[26:27], v[36:37], v[72:73] op_sel:[0,1,0]
	v_pk_fma_f32 v[36:37], v[24:25], v[36:37], v[74:75] op_sel:[0,1,0]
	v_pk_fma_f32 v[66:67], v[26:27], v[40:41], v[76:77] op_sel:[0,1,0]
	v_pk_fma_f32 v[40:41], v[24:25], v[40:41], v[78:79] op_sel:[0,1,0]
	v_pk_fma_f32 v[26:27], v[82:83], v[26:27], v[44:45] op_sel_hi:[0,1,1]
	v_pk_fma_f32 v[24:25], v[82:83], v[24:25], v[68:69] op_sel_hi:[0,1,1]
	v_pk_fma_f32 v[26:27], v[104:105], v[52:53], v[26:27] op_sel:[0,1,0]
	v_pk_fma_f32 v[24:25], v[100:101], v[52:53], v[24:25] op_sel:[0,1,0]
	v_pk_fma_f32 v[26:27], v[102:103], v[56:57], v[26:27] op_sel:[0,1,0]
	v_pk_fma_f32 v[24:25], v[96:97], v[56:57], v[24:25] op_sel:[0,1,0]
	v_pk_fma_f32 v[26:27], v[60:61], v[90:91], v[26:27] op_sel:[1,0,0]
	v_pk_fma_f32 v[24:25], v[60:61], v[88:89], v[24:25] op_sel:[1,0,0]
	v_lshl_add_u64 v[44:45], v[94:95], 0, v[118:119]
	global_store_dwordx4 v[44:45], v[24:27], off nt
	v_pk_mul_f32 v[52:53], v[98:99], v[46:47] op_sel_hi:[1,0]
	s_waitcnt vmcnt(15)
	v_pk_fma_f32 v[36:37], v[20:21], v[38:39], v[36:37] op_sel_hi:[1,0,1]
	v_pk_fma_f32 v[24:25], v[22:23], v[50:51], v[28:29] op_sel_hi:[1,0,1]
	v_pk_fma_f32 v[28:29], v[22:23], v[34:35], v[48:49] op_sel_hi:[1,0,1]
	v_pk_mul_f32 v[48:49], v[106:107], v[46:47] op_sel_hi:[1,0]
	v_pk_fma_f32 v[26:27], v[20:21], v[50:51], v[30:31] op_sel_hi:[1,0,1]
	v_pk_fma_f32 v[30:31], v[20:21], v[34:35], v[32:33] op_sel_hi:[1,0,1]
	v_pk_fma_f32 v[32:33], v[22:23], v[38:39], v[64:65] op_sel_hi:[1,0,1]
	v_pk_fma_f32 v[44:45], v[22:23], v[42:43], v[66:67] op_sel_hi:[1,0,1]
	v_pk_fma_f32 v[40:41], v[20:21], v[42:43], v[40:41] op_sel_hi:[1,0,1]
	v_pk_fma_f32 v[22:23], v[82:83], v[22:23], v[52:53] op_sel_hi:[0,1,1]
	v_pk_fma_f32 v[20:21], v[82:83], v[20:21], v[48:49] op_sel_hi:[0,1,1]
	v_pk_fma_f32 v[22:23], v[104:105], v[54:55], v[22:23] op_sel_hi:[1,0,1]
	v_pk_fma_f32 v[20:21], v[100:101], v[54:55], v[20:21] op_sel_hi:[1,0,1]
	v_pk_fma_f32 v[22:23], v[102:103], v[58:59], v[22:23] op_sel_hi:[1,0,1]
	v_pk_fma_f32 v[20:21], v[96:97], v[58:59], v[20:21] op_sel_hi:[1,0,1]
	v_pk_fma_f32 v[22:23], v[62:63], v[90:91], v[22:23] op_sel_hi:[0,1,1]
	v_pk_fma_f32 v[20:21], v[62:63], v[88:89], v[20:21] op_sel_hi:[0,1,1]
	v_lshl_add_u64 v[48:49], v[94:95], 0, v[116:117]
	global_store_dwordx4 v[48:49], v[20:23], off nt
	v_mov_b32_e32 v34, v43
	s_nop 0
	v_mov_b32_e32 v22, v51
	s_waitcnt vmcnt(15)
	v_pk_fma_f32 v[20:21], v[18:19], v[22:23], v[24:25] op_sel_hi:[1,0,1]
	v_pk_fma_f32 v[22:23], v[16:17], v[22:23], v[26:27] op_sel_hi:[1,0,1]
	v_mov_b32_e32 v26, v35
	v_pk_fma_f32 v[24:25], v[18:19], v[26:27], v[28:29] op_sel_hi:[1,0,1]
	v_pk_fma_f32 v[26:27], v[16:17], v[26:27], v[30:31] op_sel_hi:[1,0,1]
	v_mov_b32_e32 v30, v39
	v_pk_fma_f32 v[28:29], v[18:19], v[30:31], v[32:33] op_sel_hi:[1,0,1]
	v_pk_fma_f32 v[30:31], v[16:17], v[30:31], v[36:37] op_sel_hi:[1,0,1]
	v_mov_b32_e32 v36, v47
	v_pk_mul_f32 v[38:39], v[106:107], v[36:37] op_sel_hi:[1,0]
	v_pk_mul_f32 v[36:37], v[98:99], v[36:37] op_sel_hi:[1,0]
	v_pk_fma_f32 v[32:33], v[18:19], v[34:35], v[44:45] op_sel_hi:[1,0,1]
	v_pk_fma_f32 v[34:35], v[16:17], v[34:35], v[40:41] op_sel_hi:[1,0,1]
	v_pk_fma_f32 v[18:19], v[82:83], v[18:19], v[36:37] op_sel_hi:[0,1,1]
	v_pk_fma_f32 v[16:17], v[82:83], v[16:17], v[38:39] op_sel_hi:[0,1,1]
	v_mov_b32_e32 v36, v55
	v_pk_fma_f32 v[18:19], v[104:105], v[36:37], v[18:19] op_sel_hi:[1,0,1]
	v_pk_fma_f32 v[16:17], v[100:101], v[36:37], v[16:17] op_sel_hi:[1,0,1]
	v_mov_b32_e32 v36, v59
	v_pk_fma_f32 v[18:19], v[102:103], v[36:37], v[18:19] op_sel_hi:[1,0,1]
	v_pk_fma_f32 v[16:17], v[96:97], v[36:37], v[16:17] op_sel_hi:[1,0,1]
	v_mov_b32_e32 v36, v63
	v_pk_fma_f32 v[18:19], v[36:37], v[90:91], v[18:19] op_sel_hi:[0,1,1]
	v_pk_fma_f32 v[16:17], v[36:37], v[88:89], v[16:17] op_sel_hi:[0,1,1]
	v_lshl_add_u64 v[36:37], v[94:95], 0, v[114:115]
	global_store_dwordx4 v[36:37], v[16:19], off nt
	ds_read_b128 v[16:19], v87 offset:48
	s_waitcnt vmcnt(15) lgkmcnt(0)
	v_pk_fma_f32 v[44:45], v[14:15], v[16:17], v[20:21] op_sel_hi:[1,0,1]
	v_pk_fma_f32 v[46:47], v[12:13], v[16:17], v[22:23] op_sel_hi:[1,0,1]
	ds_read_b128 v[20:23], v87 offset:560
	s_waitcnt vmcnt(14)
	v_pk_fma_f32 v[44:45], v[10:11], v[16:17], v[44:45] op_sel:[0,1,0]
	v_pk_fma_f32 v[16:17], v[8:9], v[16:17], v[46:47] op_sel:[0,1,0]
	s_waitcnt lgkmcnt(0)
	v_pk_fma_f32 v[48:49], v[14:15], v[20:21], v[24:25] op_sel_hi:[1,0,1]
	v_pk_fma_f32 v[50:51], v[12:13], v[20:21], v[26:27] op_sel_hi:[1,0,1]
	ds_read_b128 v[24:27], v87 offset:1072
	v_pk_fma_f32 v[46:47], v[10:11], v[20:21], v[48:49] op_sel:[0,1,0]
	v_pk_fma_f32 v[20:21], v[8:9], v[20:21], v[50:51] op_sel:[0,1,0]
	s_waitcnt lgkmcnt(0)
	v_pk_fma_f32 v[52:53], v[14:15], v[24:25], v[28:29] op_sel_hi:[1,0,1]
	v_pk_fma_f32 v[54:55], v[12:13], v[24:25], v[30:31] op_sel_hi:[1,0,1]
	ds_read_b128 v[28:31], v87 offset:1584
	v_pk_fma_f32 v[48:49], v[10:11], v[24:25], v[52:53] op_sel:[0,1,0]
	v_pk_fma_f32 v[24:25], v[8:9], v[24:25], v[54:55] op_sel:[0,1,0]
	s_waitcnt lgkmcnt(0)
	v_pk_fma_f32 v[56:57], v[14:15], v[28:29], v[32:33] op_sel_hi:[1,0,1]
	v_pk_fma_f32 v[58:59], v[12:13], v[28:29], v[34:35] op_sel_hi:[1,0,1]
	ds_read_b128 v[32:35], v87 offset:2096
	v_pk_fma_f32 v[50:51], v[10:11], v[28:29], v[56:57] op_sel:[0,1,0]
	v_pk_fma_f32 v[28:29], v[8:9], v[28:29], v[58:59] op_sel:[0,1,0]
	s_waitcnt vmcnt(13)
	v_pk_fma_f32 v[24:25], v[4:5], v[26:27], v[24:25] op_sel_hi:[1,0,1]
	v_pk_fma_f32 v[28:29], v[4:5], v[30:31], v[28:29] op_sel_hi:[1,0,1]
	s_waitcnt lgkmcnt(0)
	v_pk_mul_f32 v[36:37], v[106:107], v[32:33] op_sel_hi:[1,0]
	v_pk_mul_f32 v[38:39], v[98:99], v[32:33] op_sel_hi:[1,0]
	v_pk_fma_f32 v[36:37], v[82:83], v[12:13], v[36:37] op_sel_hi:[0,1,1]
	v_pk_fma_f32 v[38:39], v[82:83], v[14:15], v[38:39] op_sel_hi:[0,1,1]
	ds_read_b128 v[12:15], v87 offset:2608
	v_pk_mul_f32 v[52:53], v[106:107], v[32:33] op_sel:[0,1]
	v_pk_mul_f32 v[32:33], v[98:99], v[32:33] op_sel:[0,1]
	v_pk_fma_f32 v[8:9], v[82:83], v[8:9], v[52:53] op_sel_hi:[0,1,1]
	v_pk_fma_f32 v[10:11], v[82:83], v[10:11], v[32:33] op_sel_hi:[0,1,1]
	s_waitcnt lgkmcnt(0)
	v_pk_fma_f32 v[40:41], v[104:105], v[12:13], v[38:39] op_sel_hi:[1,0,1]
	v_pk_fma_f32 v[42:43], v[100:101], v[12:13], v[36:37] op_sel_hi:[1,0,1]
	ds_read_b128 v[36:39], v87 offset:3120
	v_pk_fma_f32 v[10:11], v[104:105], v[12:13], v[10:11] op_sel:[0,1,0]
	v_pk_fma_f32 v[8:9], v[100:101], v[12:13], v[8:9] op_sel:[0,1,0]
	v_lshl_add_u64 v[12:13], v[94:95], 0, v[110:111]
	v_pk_fma_f32 v[32:33], v[6:7], v[30:31], v[50:51] op_sel_hi:[1,0,1]
	s_waitcnt lgkmcnt(0)
	v_pk_fma_f32 v[60:61], v[102:103], v[36:37], v[40:41] op_sel_hi:[1,0,1]
	v_pk_fma_f32 v[62:63], v[96:97], v[36:37], v[42:43] op_sel_hi:[1,0,1]
	ds_read_b128 v[40:43], v87 offset:3632
	v_pk_fma_f32 v[10:11], v[102:103], v[36:37], v[10:11] op_sel:[0,1,0]
	v_pk_fma_f32 v[8:9], v[96:97], v[36:37], v[8:9] op_sel:[0,1,0]
	v_pk_mul_f32 v[36:37], v[106:107], v[34:35] op_sel_hi:[1,0]
	s_waitcnt lgkmcnt(0)
	v_pk_fma_f32 v[64:65], v[40:41], v[90:91], v[60:61] op_sel_hi:[0,1,1]
	v_pk_fma_f32 v[62:63], v[40:41], v[88:89], v[62:63] op_sel_hi:[0,1,1]
	v_pk_fma_f32 v[10:11], v[40:41], v[90:91], v[10:11] op_sel:[1,0,0]
	v_pk_fma_f32 v[8:9], v[40:41], v[88:89], v[8:9] op_sel:[1,0,0]
	v_pk_mul_f32 v[40:41], v[98:99], v[34:35] op_sel_hi:[1,0]
	global_store_dwordx4 v[12:13], v[8:11], off nt
	v_pk_fma_f32 v[12:13], v[6:7], v[22:23], v[46:47] op_sel_hi:[1,0,1]
	v_lshl_add_u64 v[60:61], v[94:95], 0, v[112:113]
	v_pk_fma_f32 v[8:9], v[6:7], v[18:19], v[44:45] op_sel_hi:[1,0,1]
	v_pk_fma_f32 v[10:11], v[4:5], v[18:19], v[16:17] op_sel_hi:[1,0,1]
	v_pk_fma_f32 v[16:17], v[4:5], v[22:23], v[20:21] op_sel_hi:[1,0,1]
	v_pk_fma_f32 v[20:21], v[6:7], v[26:27], v[48:49] op_sel_hi:[1,0,1]
	v_pk_fma_f32 v[6:7], v[82:83], v[6:7], v[40:41] op_sel_hi:[0,1,1]
	v_pk_fma_f32 v[4:5], v[82:83], v[4:5], v[36:37] op_sel_hi:[0,1,1]
	v_pk_fma_f32 v[6:7], v[104:105], v[14:15], v[6:7] op_sel_hi:[1,0,1]
	v_pk_fma_f32 v[4:5], v[100:101], v[14:15], v[4:5] op_sel_hi:[1,0,1]
	v_pk_fma_f32 v[6:7], v[102:103], v[38:39], v[6:7] op_sel_hi:[1,0,1]
	v_pk_fma_f32 v[4:5], v[96:97], v[38:39], v[4:5] op_sel_hi:[1,0,1]
	v_pk_fma_f32 v[6:7], v[42:43], v[90:91], v[6:7] op_sel_hi:[0,1,1]
	v_pk_fma_f32 v[4:5], v[42:43], v[88:89], v[4:5] op_sel_hi:[0,1,1]
	v_lshl_add_u64 v[36:37], v[94:95], 0, v[108:109]
	global_store_dwordx4 v[36:37], v[4:7], off nt
	global_store_dwordx4 v[60:61], v[62:65], off nt
	s_nop 0
	v_mov_b32_e32 v4, v19
	s_waitcnt vmcnt(15)
	v_pk_fma_f32 v[6:7], v[2:3], v[4:5], v[8:9] op_sel_hi:[1,0,1]
	v_mov_b32_e32 v8, v23
	v_pk_fma_f32 v[4:5], v[0:1], v[4:5], v[10:11] op_sel_hi:[1,0,1]
	v_pk_fma_f32 v[10:11], v[2:3], v[8:9], v[12:13] op_sel_hi:[1,0,1]
	v_mov_b32_e32 v12, v27
	v_pk_fma_f32 v[8:9], v[0:1], v[8:9], v[16:17] op_sel_hi:[1,0,1]
	v_pk_fma_f32 v[18:19], v[2:3], v[12:13], v[20:21] op_sel_hi:[1,0,1]
	v_pk_fma_f32 v[16:17], v[0:1], v[12:13], v[24:25] op_sel_hi:[1,0,1]
	v_mov_b32_e32 v12, v31
	v_pk_fma_f32 v[22:23], v[2:3], v[12:13], v[32:33] op_sel_hi:[1,0,1]
	v_pk_fma_f32 v[20:21], v[0:1], v[12:13], v[28:29] op_sel_hi:[1,0,1]
	v_mov_b32_e32 v12, v35
	v_pk_mul_f32 v[24:25], v[106:107], v[12:13] op_sel_hi:[1,0]
	v_pk_mul_f32 v[12:13], v[98:99], v[12:13] op_sel_hi:[1,0]
	v_pk_fma_f32 v[0:1], v[82:83], v[0:1], v[24:25] op_sel_hi:[0,1,1]
	v_pk_fma_f32 v[2:3], v[82:83], v[2:3], v[12:13] op_sel_hi:[0,1,1]
	v_mov_b32_e32 v12, v15
	v_pk_fma_f32 v[2:3], v[104:105], v[12:13], v[2:3] op_sel_hi:[1,0,1]
	v_pk_fma_f32 v[0:1], v[100:101], v[12:13], v[0:1] op_sel_hi:[1,0,1]
	v_mov_b32_e32 v12, v39
	v_pk_fma_f32 v[2:3], v[102:103], v[12:13], v[2:3] op_sel_hi:[1,0,1]
	v_pk_fma_f32 v[0:1], v[96:97], v[12:13], v[0:1] op_sel_hi:[1,0,1]
	v_mov_b32_e32 v12, v43
	v_pk_fma_f32 v[2:3], v[12:13], v[90:91], v[2:3] op_sel_hi:[0,1,1]
	v_pk_fma_f32 v[0:1], v[12:13], v[88:89], v[0:1] op_sel_hi:[0,1,1]
	v_lshl_add_u64 v[12:13], v[94:95], 0, v[92:93]
	global_store_dwordx4 v[12:13], v[0:3], off nt
	s_nop 1
	v_lshlrev_b32_e32 v0, 12, v85
	v_add3_u32 v0, 0, v0, v176
	ds_write_b128 v0, v[4:7] offset:4352
	ds_write_b128 v0, v[8:11] offset:5376
	ds_write_b128 v0, v[16:19] offset:6400
	ds_write_b128 v0, v[20:23] offset:7424
	v_and_b32_e32 v7, 0xff, v83
	v_mov_b32_e32 v9, 0
	v_lshlrev_b32_e32 v16, 1, v7
	v_mov_b32_e32 v8, 0
	v_mov_b32_e32 v19, 0
	v_mov_b32_e32 v18, 0
	s_waitcnt lgkmcnt(0)
	s_barrier
	s_and_saveexec_b64 s[10:11], vcc
	s_cbranch_execz .LBB0_722
	v_lshl_add_u32 v37, v7, 2, 0
	global_load_ushort v27, v16, s[4:5]
	global_load_ushort v17, v16, s[6:7]
	global_load_ushort v36, v16, s[8:9]
	ds_read2st64_b32 v[8:9], v37 offset0:17 offset1:21
	ds_read2st64_b32 v[32:33], v37 offset0:33 offset1:37
	ds_read2st64_b32 v[34:35], v37 offset0:49 offset1:53
	ds_read2st64_b32 v[38:39], v37 offset0:65 offset1:69
	ds_read2st64_b32 v[40:41], v37 offset0:81 offset1:85
	ds_read2st64_b32 v[42:43], v37 offset0:97 offset1:101
	ds_read2st64_b32 v[44:45], v37 offset0:113 offset1:117
	ds_read2st64_b32 v[46:47], v37 offset0:129 offset1:133
	s_waitcnt lgkmcnt(7)
	v_add_f32_e32 v176, 0, v9
	ds_read_b32 v9, v177 offset:4096
	ds_read_b64 v[30:31], v177 offset:4112
	ds_read_b96 v[4:6], v177 offset:4128
	ds_read_b128 v[0:3], v177 offset:4144
	ds_read2st64_b32 v[24:25], v37 offset0:25 offset1:29
	ds_read2st64_b32 v[10:11], v37 offset0:41 offset1:45
	ds_read2st64_b32 v[28:29], v37 offset0:121 offset1:125
	s_waitcnt lgkmcnt(13)
	v_mov_b32_e32 v50, v33
	v_mov_b32_e32 v51, v8
	v_pk_add_f32 v[50:51], v[176:177], v[50:51]
	s_waitcnt lgkmcnt(1)
	v_mov_b32_e32 v23, v10
	v_mov_b32_e32 v26, v11
	ds_read2st64_b32 v[10:11], v37 offset0:57 offset1:61
	s_waitcnt lgkmcnt(1)
	v_mov_b32_e32 v12, v29
	v_mov_b32_e32 v52, v35
	v_mov_b32_e32 v53, v32
	v_pk_add_f32 v[32:33], v[50:51], v[52:53]
	s_waitcnt lgkmcnt(0)
	v_mov_b32_e32 v21, v10
	v_mov_b32_e32 v22, v11
	ds_read2st64_b32 v[10:11], v37 offset0:73 offset1:77
	v_mov_b32_e32 v50, v39
	v_mov_b32_e32 v51, v34
	v_pk_add_f32 v[32:33], v[32:33], v[50:51]
	v_mov_b32_e32 v34, v41
	s_waitcnt lgkmcnt(0)
	v_mov_b32_e32 v19, v10
	v_mov_b32_e32 v20, v11
	ds_read2st64_b32 v[10:11], v37 offset0:89 offset1:93
	v_mov_b32_e32 v35, v38
	v_pk_add_f32 v[32:33], v[32:33], v[34:35]
	v_mov_b32_e32 v34, v43
	v_mov_b32_e32 v35, v40
	s_waitcnt lgkmcnt(0)
	v_mov_b32_e32 v15, v10
	v_mov_b32_e32 v18, v11
	ds_read2st64_b32 v[10:11], v37 offset0:105 offset1:109
	v_pk_add_f32 v[32:33], v[32:33], v[34:35]
	v_mov_b32_e32 v34, v45
	v_mov_b32_e32 v35, v42
	v_pk_add_f32 v[32:33], v[32:33], v[34:35]
	s_waitcnt lgkmcnt(0)
	v_mov_b32_e32 v14, v11
	v_mov_b32_e32 v11, v28
	ds_read2st64_b32 v[28:29], v37 offset0:137 offset1:141
	v_mov_b32_e32 v34, v47
	v_mov_b32_e32 v35, v44
	v_mov_b32_e32 v13, v10
	v_pk_add_f32 v[32:33], v[32:33], v[34:35]
	s_waitcnt lgkmcnt(0)
	v_mov_b32_e32 v83, v28
	global_load_ushort v28, v16, s[2:3]
	v_mov_b32_e32 v10, v29
	v_mov_b32_e32 v87, v46
	v_pk_add_f32 v[34:35], v[86:87], v[32:33]
	v_mov_b32_e32 v49, v84
	v_mov_b32_e32 v8, v31
	v_cmp_lt_i32_e64 s[2:3], v204, v200
	s_waitcnt vmcnt(0)
	v_lshlrev_b32_e32 v29, 16, v28
	v_mul_f32_e32 v48, v30, v29
	v_pk_fma_f32 v[32:33], v[86:87], v[32:33], v[48:49]
	v_pk_mul_f32 v[34:35], v[48:49], v[34:35]
	v_lshlrev_b32_e32 v28, 16, v27
	v_mov_b32_e32 v33, v35
	v_pk_fma_f32 v[8:9], v[8:9], v[28:29], v[32:33]
	v_cndmask_b32_e64 v27, v197, v204, s[2:3]
	v_lshlrev_b32_e32 v38, 2, v27
	v_pk_mul_f32 v[30:31], v[8:9], v[8:9]
	ds_bpermute_b32 v32, v38, v9
	ds_bpermute_b32 v33, v38, v31
	v_cmp_lt_i32_e64 s[2:3], v205, v200
	v_mov_b32_e32 v34, v9
	v_mov_b32_e32 v35, v31
	v_cndmask_b32_e64 v27, v197, v205, s[2:3]
	v_lshlrev_b32_e32 v37, 2, v27
	s_waitcnt lgkmcnt(0)
	v_pk_add_f32 v[32:33], v[34:35], v[32:33]
	ds_bpermute_b32 v34, v37, v32
	ds_bpermute_b32 v35, v37, v33
	v_cmp_lt_i32_e64 s[2:3], v198, v200
	s_waitcnt lgkmcnt(0)
	v_pk_add_f32 v[32:33], v[32:33], v[34:35]
	v_cndmask_b32_e64 v27, v197, v198, s[2:3]
	v_lshlrev_b32_e32 v39, 2, v27
	ds_bpermute_b32 v34, v39, v32
	ds_bpermute_b32 v35, v39, v33
	v_cmp_lt_i32_e64 s[2:3], v201, v200
	s_waitcnt lgkmcnt(0)
	v_pk_add_f32 v[32:33], v[32:33], v[34:35]
	v_cndmask_b32_e64 v27, v197, v201, s[2:3]
	v_lshlrev_b32_e32 v40, 2, v27
	ds_bpermute_b32 v34, v40, v32
	ds_bpermute_b32 v35, v40, v33
	v_cmp_lt_i32_e64 s[2:3], v202, v200
	s_waitcnt lgkmcnt(0)
	v_pk_add_f32 v[32:33], v[32:33], v[34:35]
	v_cndmask_b32_e64 v27, v197, v202, s[2:3]
	v_lshlrev_b32_e32 v41, 2, v27
	ds_bpermute_b32 v34, v41, v32
	ds_bpermute_b32 v35, v41, v33
	v_cmp_lt_i32_e64 s[2:3], v203, v200
	s_waitcnt lgkmcnt(0)
	v_pk_add_f32 v[32:33], v[32:33], v[34:35]
	v_cndmask_b32_e64 v27, v197, v203, s[2:3]
	v_lshlrev_b32_e32 v42, 2, v27
	ds_bpermute_b32 v34, v42, v32
	ds_bpermute_b32 v35, v42, v33
	v_lshlrev_b32_e32 v27, 5, v85
	v_cmp_eq_u32_e64 s[2:3], 0, v81
	v_add_u32_e32 v43, 0, v27
	s_and_saveexec_b64 s[4:5], s[2:3]
	s_cbranch_execz .LBB0_715
	s_waitcnt lgkmcnt(0)
	v_pk_add_f32 v[32:33], v[32:33], v[34:35]
	ds_write_b64 v43, v[32:33] offset:4160

.Lp10_A_nopf:
	v_lshlrev_b32_e32 v204, 16, v76
	v_and_b32_e32 v205, 0xffff0000, v76
	v_lshlrev_b32_e32 v206, 16, v77
	v_and_b32_e32 v207, 0xffff0000, v77
	v_lshlrev_b32_e32 v210, 16, v78
	v_and_b32_e32 v211, 0xffff0000, v78
	v_lshlrev_b32_e32 v212, 16, v79
	v_and_b32_e32 v213, 0xffff0000, v79
	v_lshlrev_b32_e32 v214, 16, v80
	v_and_b32_e32 v215, 0xffff0000, v80
	v_lshlrev_b32_e32 v216, 16, v81
	v_and_b32_e32 v217, 0xffff0000, v81
	v_lshlrev_b32_e32 v218, 16, v82
	v_and_b32_e32 v219, 0xffff0000, v82
	v_lshlrev_b32_e32 v220, 16, v83
	v_and_b32_e32 v221, 0xffff0000, v83
	v_lshlrev_b32_e32 v222, 16, v84
	v_and_b32_e32 v223, 0xffff0000, v84
	v_lshlrev_b32_e32 v224, 16, v85
	v_and_b32_e32 v225, 0xffff0000, v85
	v_lshlrev_b32_e32 v226, 16, v86
	v_and_b32_e32 v227, 0xffff0000, v86
	v_lshlrev_b32_e32 v228, 16, v87
	v_and_b32_e32 v229, 0xffff0000, v87
	v_lshlrev_b32_e32 v230, 16, v88
	v_and_b32_e32 v231, 0xffff0000, v88
	v_lshlrev_b32_e32 v232, 16, v89
	v_and_b32_e32 v233, 0xffff0000, v89
	v_lshlrev_b32_e32 v234, 16, v90
	v_and_b32_e32 v235, 0xffff0000, v90
	v_lshlrev_b32_e32 v236, 16, v91
	v_and_b32_e32 v237, 0xffff0000, v91
	v_mul_f32_e32 v238, v204, v204
	v_mul_f32_e32 v239, v205, v205
	v_mul_f32_e32 v240, v206, v206
	v_mul_f32_e32 v241, v207, v207
	v_fmac_f32_e32 v238, v210, v210
	v_fmac_f32_e32 v239, v211, v211
	v_fmac_f32_e32 v240, v212, v212
	v_fmac_f32_e32 v241, v213, v213
	v_fmac_f32_e32 v238, v214, v214
	v_fmac_f32_e32 v239, v215, v215
	v_fmac_f32_e32 v240, v216, v216
	v_fmac_f32_e32 v241, v217, v217
	v_fmac_f32_e32 v238, v218, v218
	v_fmac_f32_e32 v239, v219, v219
	v_fmac_f32_e32 v240, v220, v220
	v_fmac_f32_e32 v241, v221, v221
	v_fmac_f32_e32 v238, v222, v222
	v_fmac_f32_e32 v239, v223, v223
	v_fmac_f32_e32 v240, v224, v224
	v_fmac_f32_e32 v241, v225, v225
	v_fmac_f32_e32 v238, v226, v226
	v_fmac_f32_e32 v239, v227, v227
	v_fmac_f32_e32 v240, v228, v228
	v_fmac_f32_e32 v241, v229, v229
	v_fmac_f32_e32 v238, v230, v230
	v_fmac_f32_e32 v239, v231, v231
	v_fmac_f32_e32 v240, v232, v232
	v_fmac_f32_e32 v241, v233, v233
	v_fmac_f32_e32 v238, v234, v234
	v_fmac_f32_e32 v239, v235, v235
	v_fmac_f32_e32 v240, v236, v236
	v_fmac_f32_e32 v241, v237, v237
	v_add_f32_e32 v238, v238, v239
	v_add_f32_e32 v240, v240, v241
	v_add_f32_e32 v238, v238, v240
	ds_bpermute_b32 v242, v5, v238
	s_waitcnt lgkmcnt(0)
	v_add_f32_e32 v238, v238, v242
	ds_bpermute_b32 v242, v6, v238
	s_waitcnt lgkmcnt(0)
	v_add_f32_e32 v238, v238, v242
	ds_bpermute_b32 v242, v7, v238
	s_waitcnt lgkmcnt(0)
	v_add_f32_e32 v238, v238, v242
	ds_bpermute_b32 v242, v8, v238
	s_waitcnt lgkmcnt(0)
	v_add_f32_e32 v238, v238, v242
	ds_bpermute_b32 v242, v9, v238
	s_waitcnt lgkmcnt(0)
	v_add_f32_e32 v238, v238, v242
	ds_bpermute_b32 v242, v10, v238
	s_waitcnt lgkmcnt(0)
	v_add_f32_e32 v238, v238, v242
	v_fmamk_f32 v238, v238, 0x3a000000, v11
	v_rsq_f32_e32 v243, v238
	s_nop 0
	v_mul_f32_e32 v204, v204, v243
	v_fmac_f32_e32 v108, v204, v12
	v_mul_f32_e32 v205, v205, v243
	v_fmac_f32_e32 v109, v205, v13
	v_mul_f32_e32 v206, v206, v243
	v_fmac_f32_e32 v110, v206, v14
	v_mul_f32_e32 v207, v207, v243
	v_fmac_f32_e32 v111, v207, v15
	v_mul_f32_e32 v210, v210, v243
	v_fmac_f32_e32 v112, v210, v16
	v_mul_f32_e32 v211, v211, v243
	v_fmac_f32_e32 v113, v211, v17
	v_mul_f32_e32 v212, v212, v243
	v_fmac_f32_e32 v114, v212, v18
	v_mul_f32_e32 v213, v213, v243
	v_fmac_f32_e32 v115, v213, v19
	v_mul_f32_e32 v214, v214, v243
	v_fmac_f32_e32 v116, v214, v20
	v_mul_f32_e32 v215, v215, v243
	v_fmac_f32_e32 v117, v215, v21
	v_mul_f32_e32 v216, v216, v243
	v_fmac_f32_e32 v118, v216, v22
	v_mul_f32_e32 v217, v217, v243
	v_fmac_f32_e32 v119, v217, v23
	v_mul_f32_e32 v218, v218, v243
	v_fmac_f32_e32 v120, v218, v24
	v_mul_f32_e32 v219, v219, v243
	v_fmac_f32_e32 v121, v219, v25
	v_mul_f32_e32 v220, v220, v243
	v_fmac_f32_e32 v122, v220, v26
	v_mul_f32_e32 v221, v221, v243
	v_fmac_f32_e32 v123, v221, v27
	v_mul_f32_e32 v222, v222, v243
	v_fmac_f32_e32 v124, v222, v28
	v_mul_f32_e32 v223, v223, v243
	v_fmac_f32_e32 v125, v223, v29
	v_mul_f32_e32 v224, v224, v243
	v_fmac_f32_e32 v126, v224, v30
	v_mul_f32_e32 v225, v225, v243
	v_fmac_f32_e32 v127, v225, v31
	v_mul_f32_e32 v226, v226, v243
	v_fmac_f32_e32 v128, v226, v32
	v_mul_f32_e32 v227, v227, v243
	v_fmac_f32_e32 v129, v227, v33
	v_mul_f32_e32 v228, v228, v243
	v_fmac_f32_e32 v130, v228, v34
	v_mul_f32_e32 v229, v229, v243
	v_fmac_f32_e32 v131, v229, v35
	v_mul_f32_e32 v230, v230, v243
	v_fmac_f32_e32 v132, v230, v36
	v_mul_f32_e32 v231, v231, v243
	v_fmac_f32_e32 v133, v231, v37
	v_mul_f32_e32 v232, v232, v243
	v_fmac_f32_e32 v134, v232, v38
	v_mul_f32_e32 v233, v233, v243
	v_fmac_f32_e32 v135, v233, v39
	v_mul_f32_e32 v234, v234, v243
	v_fmac_f32_e32 v136, v234, v40
	v_mul_f32_e32 v235, v235, v243
	v_fmac_f32_e32 v137, v235, v41
	v_mul_f32_e32 v236, v236, v243
	v_fmac_f32_e32 v138, v236, v42
	v_mul_f32_e32 v237, v237, v243
	v_fmac_f32_e32 v139, v237, v43
	v_lshlrev_b32_e32 v204, 16, v92
	v_and_b32_e32 v205, 0xffff0000, v92
	v_lshlrev_b32_e32 v206, 16, v93
	v_and_b32_e32 v207, 0xffff0000, v93
	v_lshlrev_b32_e32 v210, 16, v94
	v_and_b32_e32 v211, 0xffff0000, v94
	v_lshlrev_b32_e32 v212, 16, v95
	v_and_b32_e32 v213, 0xffff0000, v95
	v_lshlrev_b32_e32 v214, 16, v96
	v_and_b32_e32 v215, 0xffff0000, v96
	v_lshlrev_b32_e32 v216, 16, v97
	v_and_b32_e32 v217, 0xffff0000, v97
	v_lshlrev_b32_e32 v218, 16, v98
	v_and_b32_e32 v219, 0xffff0000, v98
	v_lshlrev_b32_e32 v220, 16, v99
	v_and_b32_e32 v221, 0xffff0000, v99
	v_lshlrev_b32_e32 v222, 16, v100
	v_and_b32_e32 v223, 0xffff0000, v100
	v_lshlrev_b32_e32 v224, 16, v101
	v_and_b32_e32 v225, 0xffff0000, v101
	v_lshlrev_b32_e32 v226, 16, v102
	v_and_b32_e32 v227, 0xffff0000, v102
	v_lshlrev_b32_e32 v228, 16, v103
	v_and_b32_e32 v229, 0xffff0000, v103
	v_lshlrev_b32_e32 v230, 16, v104
	v_and_b32_e32 v231, 0xffff0000, v104
	v_lshlrev_b32_e32 v232, 16, v105
	v_and_b32_e32 v233, 0xffff0000, v105
	v_lshlrev_b32_e32 v234, 16, v106
	v_and_b32_e32 v235, 0xffff0000, v106
	v_lshlrev_b32_e32 v236, 16, v107
	v_and_b32_e32 v237, 0xffff0000, v107
	v_mul_f32_e32 v238, v204, v204
	v_mul_f32_e32 v239, v205, v205
	v_mul_f32_e32 v240, v206, v206
	v_mul_f32_e32 v241, v207, v207
	v_fmac_f32_e32 v238, v210, v210
	v_fmac_f32_e32 v239, v211, v211
	v_fmac_f32_e32 v240, v212, v212
	v_fmac_f32_e32 v241, v213, v213
	v_fmac_f32_e32 v238, v214, v214
	v_fmac_f32_e32 v239, v215, v215
	v_fmac_f32_e32 v240, v216, v216
	v_fmac_f32_e32 v241, v217, v217
	v_fmac_f32_e32 v238, v218, v218
	v_fmac_f32_e32 v239, v219, v219
	v_fmac_f32_e32 v240, v220, v220
	v_fmac_f32_e32 v241, v221, v221
	v_fmac_f32_e32 v238, v222, v222
	v_fmac_f32_e32 v239, v223, v223
	v_fmac_f32_e32 v240, v224, v224
	v_fmac_f32_e32 v241, v225, v225
	v_fmac_f32_e32 v238, v226, v226
	v_fmac_f32_e32 v239, v227, v227
	v_fmac_f32_e32 v240, v228, v228
	v_fmac_f32_e32 v241, v229, v229
	v_fmac_f32_e32 v238, v230, v230
	v_fmac_f32_e32 v239, v231, v231
	v_fmac_f32_e32 v240, v232, v232
	v_fmac_f32_e32 v241, v233, v233
	v_fmac_f32_e32 v238, v234, v234
	v_fmac_f32_e32 v239, v235, v235
	v_fmac_f32_e32 v240, v236, v236
	v_fmac_f32_e32 v241, v237, v237
	v_add_f32_e32 v238, v238, v239
	v_add_f32_e32 v240, v240, v241
	v_add_f32_e32 v238, v238, v240
	ds_bpermute_b32 v242, v5, v238
	s_waitcnt lgkmcnt(0)
	v_add_f32_e32 v238, v238, v242
	ds_bpermute_b32 v242, v6, v238
	s_waitcnt lgkmcnt(0)
	v_add_f32_e32 v238, v238, v242
	ds_bpermute_b32 v242, v7, v238
	s_waitcnt lgkmcnt(0)
	v_add_f32_e32 v238, v238, v242
	ds_bpermute_b32 v242, v8, v238
	s_waitcnt lgkmcnt(0)
	v_add_f32_e32 v238, v238, v242
	ds_bpermute_b32 v242, v9, v238
	s_waitcnt lgkmcnt(0)
	v_add_f32_e32 v238, v238, v242
	ds_bpermute_b32 v242, v10, v238
	s_waitcnt lgkmcnt(0)
	v_add_f32_e32 v238, v238, v242
	v_fmamk_f32 v238, v238, 0x3a000000, v11
	v_rsq_f32_e32 v243, v238
	s_nop 0
	v_mul_f32_e32 v204, v204, v243
	v_fmac_f32_e32 v108, v204, v44
	v_mul_f32_e32 v205, v205, v243
	v_fmac_f32_e32 v109, v205, v45
	v_mul_f32_e32 v206, v206, v243
	v_fmac_f32_e32 v110, v206, v46
	v_mul_f32_e32 v207, v207, v243
	v_fmac_f32_e32 v111, v207, v47
	v_mul_f32_e32 v210, v210, v243
	v_fmac_f32_e32 v112, v210, v48
	v_mul_f32_e32 v211, v211, v243
	v_fmac_f32_e32 v113, v211, v49
	v_mul_f32_e32 v212, v212, v243
	v_fmac_f32_e32 v114, v212, v50
	v_mul_f32_e32 v213, v213, v243
	v_fmac_f32_e32 v115, v213, v51
	v_mul_f32_e32 v214, v214, v243
	v_fmac_f32_e32 v116, v214, v52
	v_mul_f32_e32 v215, v215, v243
	v_fmac_f32_e32 v117, v215, v53
	v_mul_f32_e32 v216, v216, v243
	v_fmac_f32_e32 v118, v216, v54
	v_mul_f32_e32 v217, v217, v243
	v_fmac_f32_e32 v119, v217, v55
	v_mul_f32_e32 v218, v218, v243
	v_fmac_f32_e32 v120, v218, v56
	v_mul_f32_e32 v219, v219, v243
	v_fmac_f32_e32 v121, v219, v57
	v_mul_f32_e32 v220, v220, v243
	v_fmac_f32_e32 v122, v220, v58
	v_mul_f32_e32 v221, v221, v243
	v_fmac_f32_e32 v123, v221, v59
	v_mul_f32_e32 v222, v222, v243
	v_fmac_f32_e32 v124, v222, v60
	v_mul_f32_e32 v223, v223, v243
	v_fmac_f32_e32 v125, v223, v61
	v_mul_f32_e32 v224, v224, v243
	v_fmac_f32_e32 v126, v224, v62
	v_mul_f32_e32 v225, v225, v243
	v_fmac_f32_e32 v127, v225, v63
	v_mul_f32_e32 v226, v226, v243
	v_fmac_f32_e32 v128, v226, v64
	v_mul_f32_e32 v227, v227, v243
	v_fmac_f32_e32 v129, v227, v65
	v_mul_f32_e32 v228, v228, v243
	v_fmac_f32_e32 v130, v228, v66
	v_mul_f32_e32 v229, v229, v243
	v_fmac_f32_e32 v131, v229, v67
	v_mul_f32_e32 v230, v230, v243
	v_fmac_f32_e32 v132, v230, v68
	v_mul_f32_e32 v231, v231, v243
	v_fmac_f32_e32 v133, v231, v69
	v_mul_f32_e32 v232, v232, v243
	v_fmac_f32_e32 v134, v232, v70
	v_mul_f32_e32 v233, v233, v243
	v_fmac_f32_e32 v135, v233, v71
	v_mul_f32_e32 v234, v234, v243
	v_fmac_f32_e32 v136, v234, v72
	v_mul_f32_e32 v235, v235, v243
	v_fmac_f32_e32 v137, v235, v73
	v_mul_f32_e32 v236, v236, v243
	v_fmac_f32_e32 v138, v236, v74
	v_mul_f32_e32 v237, v237, v243
	v_fmac_f32_e32 v139, v237, v75
	s_lshl_b32 s4, s2, 13
	s_add_u32 s14, s22, s4
	s_addc_u32 s15, s23, 0
	global_store_dwordx4 v1, v[108:111], s[14:15] nt
	global_store_dwordx4 v1, v[112:115], s[14:15] offset:16 nt
	global_store_dwordx4 v1, v[116:119], s[14:15] offset:2048 nt
	global_store_dwordx4 v1, v[120:123], s[14:15] offset:2064 nt
	global_store_dwordx4 v2, v[124:127], s[14:15] nt
	global_store_dwordx4 v2, v[128:131], s[14:15] offset:16 nt
	global_store_dwordx4 v2, v[132:135], s[14:15] offset:2048 nt
	global_store_dwordx4 v2, v[136:139], s[14:15] offset:2064 nt
	s_mov_b32 s2, s29
	s_cmp_ge_u32 s2, 0x2080
	s_cbranch_scc1 .Lp10_done

.Lp10_B_nopf:
	v_lshlrev_b32_e32 v204, 16, v140
	v_and_b32_e32 v205, 0xffff0000, v140
	v_lshlrev_b32_e32 v206, 16, v141
	v_and_b32_e32 v207, 0xffff0000, v141
	v_lshlrev_b32_e32 v210, 16, v142
	v_and_b32_e32 v211, 0xffff0000, v142
	v_lshlrev_b32_e32 v212, 16, v143
	v_and_b32_e32 v213, 0xffff0000, v143
	v_lshlrev_b32_e32 v214, 16, v144
	v_and_b32_e32 v215, 0xffff0000, v144
	v_lshlrev_b32_e32 v216, 16, v145
	v_and_b32_e32 v217, 0xffff0000, v145
	v_lshlrev_b32_e32 v218, 16, v146
	v_and_b32_e32 v219, 0xffff0000, v146
	v_lshlrev_b32_e32 v220, 16, v147
	v_and_b32_e32 v221, 0xffff0000, v147
	v_lshlrev_b32_e32 v222, 16, v148
	v_and_b32_e32 v223, 0xffff0000, v148
	v_lshlrev_b32_e32 v224, 16, v149
	v_and_b32_e32 v225, 0xffff0000, v149
	v_lshlrev_b32_e32 v226, 16, v150
	v_and_b32_e32 v227, 0xffff0000, v150
	v_lshlrev_b32_e32 v228, 16, v151
	v_and_b32_e32 v229, 0xffff0000, v151
	v_lshlrev_b32_e32 v230, 16, v152
	v_and_b32_e32 v231, 0xffff0000, v152
	v_lshlrev_b32_e32 v232, 16, v153
	v_and_b32_e32 v233, 0xffff0000, v153
	v_lshlrev_b32_e32 v234, 16, v154
	v_and_b32_e32 v235, 0xffff0000, v154
	v_lshlrev_b32_e32 v236, 16, v155
	v_and_b32_e32 v237, 0xffff0000, v155
	v_mul_f32_e32 v238, v204, v204
	v_mul_f32_e32 v239, v205, v205
	v_mul_f32_e32 v240, v206, v206
	v_mul_f32_e32 v241, v207, v207
	v_fmac_f32_e32 v238, v210, v210
	v_fmac_f32_e32 v239, v211, v211
	v_fmac_f32_e32 v240, v212, v212
	v_fmac_f32_e32 v241, v213, v213
	v_fmac_f32_e32 v238, v214, v214
	v_fmac_f32_e32 v239, v215, v215
	v_fmac_f32_e32 v240, v216, v216
	v_fmac_f32_e32 v241, v217, v217
	v_fmac_f32_e32 v238, v218, v218
	v_fmac_f32_e32 v239, v219, v219
	v_fmac_f32_e32 v240, v220, v220
	v_fmac_f32_e32 v241, v221, v221
	v_fmac_f32_e32 v238, v222, v222
	v_fmac_f32_e32 v239, v223, v223
	v_fmac_f32_e32 v240, v224, v224
	v_fmac_f32_e32 v241, v225, v225
	v_fmac_f32_e32 v238, v226, v226
	v_fmac_f32_e32 v239, v227, v227
	v_fmac_f32_e32 v240, v228, v228
	v_fmac_f32_e32 v241, v229, v229
	v_fmac_f32_e32 v238, v230, v230
	v_fmac_f32_e32 v239, v231, v231
	v_fmac_f32_e32 v240, v232, v232
	v_fmac_f32_e32 v241, v233, v233
	v_fmac_f32_e32 v238, v234, v234
	v_fmac_f32_e32 v239, v235, v235
	v_fmac_f32_e32 v240, v236, v236
	v_fmac_f32_e32 v241, v237, v237
	v_add_f32_e32 v238, v238, v239
	v_add_f32_e32 v240, v240, v241
	v_add_f32_e32 v238, v238, v240
	ds_bpermute_b32 v242, v5, v238
	s_waitcnt lgkmcnt(0)
	v_add_f32_e32 v238, v238, v242
	ds_bpermute_b32 v242, v6, v238
	s_waitcnt lgkmcnt(0)
	v_add_f32_e32 v238, v238, v242
	ds_bpermute_b32 v242, v7, v238
	s_waitcnt lgkmcnt(0)
	v_add_f32_e32 v238, v238, v242
	ds_bpermute_b32 v242, v8, v238
	s_waitcnt lgkmcnt(0)
	v_add_f32_e32 v238, v238, v242
	ds_bpermute_b32 v242, v9, v238
	s_waitcnt lgkmcnt(0)
	v_add_f32_e32 v238, v238, v242
	ds_bpermute_b32 v242, v10, v238
	s_waitcnt lgkmcnt(0)
	v_add_f32_e32 v238, v238, v242
	v_fmamk_f32 v238, v238, 0x3a000000, v11
	v_rsq_f32_e32 v243, v238
	s_nop 0
	v_mul_f32_e32 v204, v204, v243
	v_fmac_f32_e32 v172, v204, v12
	v_mul_f32_e32 v205, v205, v243
	v_fmac_f32_e32 v173, v205, v13
	v_mul_f32_e32 v206, v206, v243
	v_fmac_f32_e32 v174, v206, v14
	v_mul_f32_e32 v207, v207, v243
	v_fmac_f32_e32 v175, v207, v15
	v_mul_f32_e32 v210, v210, v243
	v_fmac_f32_e32 v176, v210, v16
	v_mul_f32_e32 v211, v211, v243
	v_fmac_f32_e32 v177, v211, v17
	v_mul_f32_e32 v212, v212, v243
	v_fmac_f32_e32 v178, v212, v18
	v_mul_f32_e32 v213, v213, v243
	v_fmac_f32_e32 v179, v213, v19
	v_mul_f32_e32 v214, v214, v243
	v_fmac_f32_e32 v180, v214, v20
	v_mul_f32_e32 v215, v215, v243
	v_fmac_f32_e32 v181, v215, v21
	v_mul_f32_e32 v216, v216, v243
	v_fmac_f32_e32 v182, v216, v22
	v_mul_f32_e32 v217, v217, v243
	v_fmac_f32_e32 v183, v217, v23
	v_mul_f32_e32 v218, v218, v243
	v_fmac_f32_e32 v184, v218, v24
	v_mul_f32_e32 v219, v219, v243
	v_fmac_f32_e32 v185, v219, v25
	v_mul_f32_e32 v220, v220, v243
	v_fmac_f32_e32 v186, v220, v26
	v_mul_f32_e32 v221, v221, v243
	v_fmac_f32_e32 v187, v221, v27
	v_mul_f32_e32 v222, v222, v243
	v_fmac_f32_e32 v188, v222, v28
	v_mul_f32_e32 v223, v223, v243
	v_fmac_f32_e32 v189, v223, v29
	v_mul_f32_e32 v224, v224, v243
	v_fmac_f32_e32 v190, v224, v30
	v_mul_f32_e32 v225, v225, v243
	v_fmac_f32_e32 v191, v225, v31
	v_mul_f32_e32 v226, v226, v243
	v_fmac_f32_e32 v192, v226, v32
	v_mul_f32_e32 v227, v227, v243
	v_fmac_f32_e32 v193, v227, v33
	v_mul_f32_e32 v228, v228, v243
	v_fmac_f32_e32 v194, v228, v34
	v_mul_f32_e32 v229, v229, v243
	v_fmac_f32_e32 v195, v229, v35
	v_mul_f32_e32 v230, v230, v243
	v_fmac_f32_e32 v196, v230, v36
	v_mul_f32_e32 v231, v231, v243
	v_fmac_f32_e32 v197, v231, v37
	v_mul_f32_e32 v232, v232, v243
	v_fmac_f32_e32 v198, v232, v38
	v_mul_f32_e32 v233, v233, v243
	v_fmac_f32_e32 v199, v233, v39
	v_mul_f32_e32 v234, v234, v243
	v_fmac_f32_e32 v200, v234, v40
	v_mul_f32_e32 v235, v235, v243
	v_fmac_f32_e32 v201, v235, v41
	v_mul_f32_e32 v236, v236, v243
	v_fmac_f32_e32 v202, v236, v42
	v_mul_f32_e32 v237, v237, v243
	v_fmac_f32_e32 v203, v237, v43
	v_lshlrev_b32_e32 v204, 16, v156
	v_and_b32_e32 v205, 0xffff0000, v156
	v_lshlrev_b32_e32 v206, 16, v157
	v_and_b32_e32 v207, 0xffff0000, v157
	v_lshlrev_b32_e32 v210, 16, v158
	v_and_b32_e32 v211, 0xffff0000, v158
	v_lshlrev_b32_e32 v212, 16, v159
	v_and_b32_e32 v213, 0xffff0000, v159
	v_lshlrev_b32_e32 v214, 16, v160
	v_and_b32_e32 v215, 0xffff0000, v160
	v_lshlrev_b32_e32 v216, 16, v161
	v_and_b32_e32 v217, 0xffff0000, v161
	v_lshlrev_b32_e32 v218, 16, v162
	v_and_b32_e32 v219, 0xffff0000, v162
	v_lshlrev_b32_e32 v220, 16, v163
	v_and_b32_e32 v221, 0xffff0000, v163
	v_lshlrev_b32_e32 v222, 16, v164
	v_and_b32_e32 v223, 0xffff0000, v164
	v_lshlrev_b32_e32 v224, 16, v165
	v_and_b32_e32 v225, 0xffff0000, v165
	v_lshlrev_b32_e32 v226, 16, v166
	v_and_b32_e32 v227, 0xffff0000, v166
	v_lshlrev_b32_e32 v228, 16, v167
	v_and_b32_e32 v229, 0xffff0000, v167
	v_lshlrev_b32_e32 v230, 16, v168
	v_and_b32_e32 v231, 0xffff0000, v168
	v_lshlrev_b32_e32 v232, 16, v169
	v_and_b32_e32 v233, 0xffff0000, v169
	v_lshlrev_b32_e32 v234, 16, v170
	v_and_b32_e32 v235, 0xffff0000, v170
	v_lshlrev_b32_e32 v236, 16, v171
	v_and_b32_e32 v237, 0xffff0000, v171
	v_mul_f32_e32 v238, v204, v204
	v_mul_f32_e32 v239, v205, v205
	v_mul_f32_e32 v240, v206, v206
	v_mul_f32_e32 v241, v207, v207
	v_fmac_f32_e32 v238, v210, v210
	v_fmac_f32_e32 v239, v211, v211
	v_fmac_f32_e32 v240, v212, v212
	v_fmac_f32_e32 v241, v213, v213
	v_fmac_f32_e32 v238, v214, v214
	v_fmac_f32_e32 v239, v215, v215
	v_fmac_f32_e32 v240, v216, v216
	v_fmac_f32_e32 v241, v217, v217
	v_fmac_f32_e32 v238, v218, v218
	v_fmac_f32_e32 v239, v219, v219
	v_fmac_f32_e32 v240, v220, v220
	v_fmac_f32_e32 v241, v221, v221
	v_fmac_f32_e32 v238, v222, v222
	v_fmac_f32_e32 v239, v223, v223
	v_fmac_f32_e32 v240, v224, v224
	v_fmac_f32_e32 v241, v225, v225
	v_fmac_f32_e32 v238, v226, v226
	v_fmac_f32_e32 v239, v227, v227
	v_fmac_f32_e32 v240, v228, v228
	v_fmac_f32_e32 v241, v229, v229
	v_fmac_f32_e32 v238, v230, v230
	v_fmac_f32_e32 v239, v231, v231
	v_fmac_f32_e32 v240, v232, v232
	v_fmac_f32_e32 v241, v233, v233
	v_fmac_f32_e32 v238, v234, v234
	v_fmac_f32_e32 v239, v235, v235
	v_fmac_f32_e32 v240, v236, v236
	v_fmac_f32_e32 v241, v237, v237
	v_add_f32_e32 v238, v238, v239
	v_add_f32_e32 v240, v240, v241
	v_add_f32_e32 v238, v238, v240
	ds_bpermute_b32 v242, v5, v238
	s_waitcnt lgkmcnt(0)
	v_add_f32_e32 v238, v238, v242
	ds_bpermute_b32 v242, v6, v238
	s_waitcnt lgkmcnt(0)
	v_add_f32_e32 v238, v238, v242
	ds_bpermute_b32 v242, v7, v238
	s_waitcnt lgkmcnt(0)
	v_add_f32_e32 v238, v238, v242
	ds_bpermute_b32 v242, v8, v238
	s_waitcnt lgkmcnt(0)
	v_add_f32_e32 v238, v238, v242
	ds_bpermute_b32 v242, v9, v238
	s_waitcnt lgkmcnt(0)
	v_add_f32_e32 v238, v238, v242
	ds_bpermute_b32 v242, v10, v238
	s_waitcnt lgkmcnt(0)
	v_add_f32_e32 v238, v238, v242
	v_fmamk_f32 v238, v238, 0x3a000000, v11
	v_rsq_f32_e32 v243, v238
	s_nop 0
	v_mul_f32_e32 v204, v204, v243
	v_fmac_f32_e32 v172, v204, v44
	v_mul_f32_e32 v205, v205, v243
	v_fmac_f32_e32 v173, v205, v45
	v_mul_f32_e32 v206, v206, v243
	v_fmac_f32_e32 v174, v206, v46
	v_mul_f32_e32 v207, v207, v243
	v_fmac_f32_e32 v175, v207, v47
	v_mul_f32_e32 v210, v210, v243
	v_fmac_f32_e32 v176, v210, v48
	v_mul_f32_e32 v211, v211, v243
	v_fmac_f32_e32 v177, v211, v49
	v_mul_f32_e32 v212, v212, v243
	v_fmac_f32_e32 v178, v212, v50
	v_mul_f32_e32 v213, v213, v243
	v_fmac_f32_e32 v179, v213, v51
	v_mul_f32_e32 v214, v214, v243
	v_fmac_f32_e32 v180, v214, v52
	v_mul_f32_e32 v215, v215, v243
	v_fmac_f32_e32 v181, v215, v53
	v_mul_f32_e32 v216, v216, v243
	v_fmac_f32_e32 v182, v216, v54
	v_mul_f32_e32 v217, v217, v243
	v_fmac_f32_e32 v183, v217, v55
	v_mul_f32_e32 v218, v218, v243
	v_fmac_f32_e32 v184, v218, v56
	v_mul_f32_e32 v219, v219, v243
	v_fmac_f32_e32 v185, v219, v57
	v_mul_f32_e32 v220, v220, v243
	v_fmac_f32_e32 v186, v220, v58
	v_mul_f32_e32 v221, v221, v243
	v_fmac_f32_e32 v187, v221, v59
	v_mul_f32_e32 v222, v222, v243
	v_fmac_f32_e32 v188, v222, v60
	v_mul_f32_e32 v223, v223, v243
	v_fmac_f32_e32 v189, v223, v61
	v_mul_f32_e32 v224, v224, v243
	v_fmac_f32_e32 v190, v224, v62
	v_mul_f32_e32 v225, v225, v243
	v_fmac_f32_e32 v191, v225, v63
	v_mul_f32_e32 v226, v226, v243
	v_fmac_f32_e32 v192, v226, v64
	v_mul_f32_e32 v227, v227, v243
	v_fmac_f32_e32 v193, v227, v65
	v_mul_f32_e32 v228, v228, v243
	v_fmac_f32_e32 v194, v228, v66
	v_mul_f32_e32 v229, v229, v243
	v_fmac_f32_e32 v195, v229, v67
	v_mul_f32_e32 v230, v230, v243
	v_fmac_f32_e32 v196, v230, v68
	v_mul_f32_e32 v231, v231, v243
	v_fmac_f32_e32 v197, v231, v69
	v_mul_f32_e32 v232, v232, v243
	v_fmac_f32_e32 v198, v232, v70
	v_mul_f32_e32 v233, v233, v243
	v_fmac_f32_e32 v199, v233, v71
	v_mul_f32_e32 v234, v234, v243
	v_fmac_f32_e32 v200, v234, v72
	v_mul_f32_e32 v235, v235, v243
	v_fmac_f32_e32 v201, v235, v73
	v_mul_f32_e32 v236, v236, v243
	v_fmac_f32_e32 v202, v236, v74
	v_mul_f32_e32 v237, v237, v243
	v_fmac_f32_e32 v203, v237, v75
	s_lshl_b32 s4, s2, 13
	s_add_u32 s14, s22, s4
	s_addc_u32 s15, s23, 0
	global_store_dwordx4 v1, v[172:175], s[14:15] nt
	global_store_dwordx4 v1, v[176:179], s[14:15] offset:16 nt
	global_store_dwordx4 v1, v[180:183], s[14:15] offset:2048 nt
	global_store_dwordx4 v1, v[184:187], s[14:15] offset:2064 nt
	global_store_dwordx4 v2, v[188:191], s[14:15] nt
	global_store_dwordx4 v2, v[192:195], s[14:15] offset:16 nt
	global_store_dwordx4 v2, v[196:199], s[14:15] offset:2048 nt
	global_store_dwordx4 v2, v[200:203], s[14:15] offset:2064 nt
	s_mov_b32 s2, s29
	s_cmp_ge_u32 s2, 0x2080
	s_cbranch_scc0 .Lp10_A
